# grid-barrier census (first barrier): the 16 per-XCD counter loads issued back-to-back with one wait instead of load-wait-add chains
# speedup vs baseline: 1.0053x; 1.0053x over previous
; __device__ __forceinline__ unsigned xb_ld(unsigned* p)              { return __hip_atomic_load(p, __ATOMIC_RELAXED, __HIP_MEMORY_SCOPE_AGENT); }
; __device__ __forceinline__ void xcd_barrier_complete(unsigned* bar, unsigned x, unsigned& nloc, unsigned& nx) {
;   const unsigned G = gridDim.x * gridDim.y * gridDim.z;
;   unsigned sum, cnt, mine, sp = 0u;
;   for (;;) {
;     sum = 0u; cnt = 0u; mine = 0u;
; #pragma unroll
;     for (unsigned j = 0; j < 16; ++j) { const unsigned c = xb_ld(&bar[XB_XCNT(j)]); sum += c; cnt += (c > 0u) ? 1u : 0u; mine = (j == x) ? c : mine; }
;     if (sum == G) break;
;     __builtin_amdgcn_s_sleep(1);
;     if ((++sp & 255u) == 0u) { if (xb_ld(&bar[XB_TMO])) break; if (sp > XB_SPIN_CAP) { atomicAdd(&bar[XB_TMO], 1u); break; } }
;   }
;   nloc = mine > 0u ? mine : 1u; nx = cnt > 0u ? cnt : 1u;
; }
.LBB0_365:
	v_readlane_b32 s6, v253, 16
	v_readlane_b32 s7, v253, 17
	s_mov_b64 s[42:43], -1
	s_nop 3
	global_load_dword v0, v201, s[6:7] sc1
	v_readlane_b32 s6, v253, 12
	v_readlane_b32 s7, v253, 13
	s_nop 4
	global_load_dword v1, v201, s[6:7] sc1
	v_readlane_b32 s6, v253, 10
	v_readlane_b32 s7, v253, 11
	s_nop 1
	s_nop 2
	global_load_dword v2, v201, s[6:7] sc1
	v_readlane_b32 s6, v253, 8
	v_readlane_b32 s7, v253, 9
	s_nop 1
	s_nop 2
	global_load_dword v3, v201, s[6:7] sc1
	v_readlane_b32 s6, v253, 49
	v_readlane_b32 s7, v253, 50
	s_nop 1
	s_nop 2
	global_load_dword v4, v201, s[6:7] sc1
	v_readlane_b32 s6, v253, 51
	v_readlane_b32 s7, v253, 52
	s_nop 1
	s_nop 2
	global_load_dword v5, v201, s[6:7] sc1
	v_readlane_b32 s6, v253, 53
	v_readlane_b32 s7, v253, 54
	s_nop 1
	s_nop 2
	global_load_dword v6, v201, s[6:7] sc1
	v_readlane_b32 s6, v253, 55
	v_readlane_b32 s7, v253, 56
	s_nop 1
	s_nop 2
	global_load_dword v7, v201, s[6:7] sc1
	v_readlane_b32 s6, v253, 57
	v_readlane_b32 s7, v253, 58
	s_nop 1
	s_nop 2
	global_load_dword v8, v201, s[6:7] sc1
	v_readlane_b32 s6, v253, 59
	v_readlane_b32 s7, v253, 60
	s_nop 1
	s_nop 2
	global_load_dword v9, v201, s[6:7] sc1
	v_readlane_b32 s6, v253, 61
	v_readlane_b32 s7, v253, 62
	s_nop 1
	s_nop 2
	global_load_dword v10, v201, s[6:7] sc1
	v_readlane_b32 s6, v253, 63
	v_readlane_b32 s7, v254, 0
	s_nop 1
	s_nop 2
	global_load_dword v11, v201, s[6:7] sc1
	v_readlane_b32 s6, v254, 1
	v_readlane_b32 s7, v254, 2
	s_nop 1
	s_nop 2
	global_load_dword v12, v201, s[6:7] sc1
	v_readlane_b32 s6, v254, 3
	v_readlane_b32 s7, v254, 4
	s_nop 1
	s_nop 2
	global_load_dword v13, v201, s[6:7] sc1
	v_readlane_b32 s6, v254, 5
	v_readlane_b32 s7, v254, 6
	s_nop 1
	s_nop 2
	global_load_dword v14, v201, s[6:7] sc1
	v_readlane_b32 s6, v254, 7
	v_readlane_b32 s7, v254, 8
	s_nop 1
	s_nop 2
	global_load_dword v15, v201, s[6:7] sc1
	s_mov_b64 s[6:7], -1
	s_waitcnt vmcnt(0)
	v_add_u32_e32 v16, v1, v0
	v_add_u32_e32 v16, v16, v2
	v_add_u32_e32 v16, v16, v3
	v_add_u32_e32 v16, v16, v4
	v_add_u32_e32 v16, v16, v5
	v_add_u32_e32 v16, v16, v6
	v_add_u32_e32 v16, v16, v7
	v_add_u32_e32 v16, v16, v8
	v_add_u32_e32 v16, v16, v9
	v_add_u32_e32 v16, v16, v10
	v_add_u32_e32 v16, v16, v11
	v_add_u32_e32 v16, v16, v12
	v_add_u32_e32 v16, v16, v13
	v_add_u32_e32 v16, v16, v14
	v_add_u32_e32 v16, v16, v15
	v_cmp_eq_u32_e32 vcc, s3, v16
	s_cbranch_vccnz .LBB0_364
	s_and_b32 s6, s8, 0xff
	s_cmp_eq_u32 s6, 0
	s_mov_b64 s[6:7], -1
	s_mov_b64 s[44:45], -1
	s_sleep 1
	s_cbranch_scc1 .LBB0_369
	s_and_b64 vcc, exec, s[44:45]
	s_cbranch_vccz .LBB0_364
